# nt on the attention / dilated-attention O stores (consumed by the merge pass after the whole phase)
# speedup vs baseline: 1.0074x; 1.0074x over previous
.LBB0_375:
	s_or_b64 exec, exec, s[54:55]
	s_waitcnt lgkmcnt(0)
	ds_read_b128 v[34:37], v89 offset:128
	ds_read_b128 v[38:41], v89 offset:160
	s_lshl_b64 s[0:1], s[52:53], 24
	s_add_u32 s0, s19, s0
	s_addc_u32 s1, s20, s1
	s_waitcnt lgkmcnt(1)
	v_rcp_f32_e32 v42, v34
	s_lshl_b32 s46, s46, 12
	s_add_i32 s46, s46, 0
	v_rcp_f32_e32 v43, v35
	s_add_i32 s46, s46, 0x18800
	v_lshlrev_b32_e32 v50, 1, v86
	v_lshlrev_b32_e32 v51, 9, v88
	v_mul_f32_e32 v2, v2, v42
	v_add3_u32 v50, s46, v50, v51
	v_cvt_pk_bf16_f32 v2, v2, s0
	ds_write_b16 v50, v2
	v_mul_f32_e32 v2, v18, v42
	v_cvt_pk_bf16_f32 v2, v2, s0
	v_rcp_f32_e32 v44, v36
	ds_write_b16 v50, v2 offset:64
	v_mul_f32_e32 v2, v3, v43
	v_cvt_pk_bf16_f32 v2, v2, s0
	ds_write_b16 v50, v2 offset:128
	v_mul_f32_e32 v2, v19, v43
	v_cvt_pk_bf16_f32 v2, v2, s0
	v_rcp_f32_e32 v45, v37
	ds_write_b16 v50, v2 offset:192
	v_mul_f32_e32 v2, v4, v44
	v_cvt_pk_bf16_f32 v2, v2, s0
	ds_write_b16 v50, v2 offset:256
	v_mul_f32_e32 v2, v20, v44
	v_cvt_pk_bf16_f32 v2, v2, s0
	s_waitcnt lgkmcnt(5)
	v_rcp_f32_e32 v46, v38
	ds_write_b16 v50, v2 offset:320
	v_mul_f32_e32 v2, v5, v45
	v_cvt_pk_bf16_f32 v2, v2, s0
	ds_write_b16 v50, v2 offset:384
	v_mul_f32_e32 v2, v21, v45
	v_cvt_pk_bf16_f32 v2, v2, s0
	v_rcp_f32_e32 v47, v39
	ds_write_b16 v50, v2 offset:448
	v_mul_f32_e32 v2, v6, v46
	v_cvt_pk_bf16_f32 v2, v2, s0
	ds_write_b16 v50, v2 offset:1024
	v_mul_f32_e32 v2, v22, v46
	v_cvt_pk_bf16_f32 v2, v2, s0
	v_rcp_f32_e32 v48, v40
	ds_write_b16 v50, v2 offset:1088
	v_mul_f32_e32 v2, v7, v47
	v_cvt_pk_bf16_f32 v2, v2, s0
	ds_write_b16 v50, v2 offset:1152
	v_mul_f32_e32 v2, v23, v47
	ds_read_b128 v[34:37], v89 offset:192
	v_cvt_pk_bf16_f32 v2, v2, s0
	v_rcp_f32_e32 v49, v41
	ds_write_b16 v50, v2 offset:1216
	v_mul_f32_e32 v2, v8, v48
	v_cvt_pk_bf16_f32 v2, v2, s0
	ds_write_b16 v50, v2 offset:1280
	v_mul_f32_e32 v2, v24, v48
	v_cvt_pk_bf16_f32 v2, v2, s0
	ds_read_b128 v[38:41], v89 offset:224
	s_waitcnt lgkmcnt(3)
	v_rcp_f32_e32 v34, v34
	ds_write_b16 v50, v2 offset:1344
	v_mul_f32_e32 v2, v9, v49
	v_cvt_pk_bf16_f32 v2, v2, s0
	ds_write_b16 v50, v2 offset:1408
	v_mul_f32_e32 v2, v25, v49
	v_cvt_pk_bf16_f32 v2, v2, s0
	v_rcp_f32_e32 v35, v35
	ds_write_b16 v50, v2 offset:1472
	v_mul_f32_e32 v2, v10, v34
	v_cvt_pk_bf16_f32 v2, v2, s0
	ds_write_b16 v50, v2 offset:2048
	v_mul_f32_e32 v2, v26, v34
	v_cvt_pk_bf16_f32 v2, v2, s0
	v_rcp_f32_e32 v36, v36
	ds_write_b16 v50, v2 offset:2112
	v_mul_f32_e32 v2, v11, v35
	v_cvt_pk_bf16_f32 v2, v2, s0
	ds_write_b16 v50, v2 offset:2176
	v_mul_f32_e32 v2, v27, v35
	v_cvt_pk_bf16_f32 v2, v2, s0
	v_rcp_f32_e32 v37, v37
	ds_write_b16 v50, v2 offset:2240
	v_mul_f32_e32 v2, v12, v36
	v_cvt_pk_bf16_f32 v2, v2, s0
	ds_write_b16 v50, v2 offset:2304
	v_mul_f32_e32 v2, v28, v36
	v_cvt_pk_bf16_f32 v2, v2, s0
	s_waitcnt lgkmcnt(8)
	v_rcp_f32_e32 v38, v38
	ds_write_b16 v50, v2 offset:2368
	v_mul_f32_e32 v2, v13, v37
	v_cvt_pk_bf16_f32 v2, v2, s0
	ds_write_b16 v50, v2 offset:2432
	v_mul_f32_e32 v2, v29, v37
	v_cvt_pk_bf16_f32 v2, v2, s0
	v_rcp_f32_e32 v39, v39
	ds_write_b16 v50, v2 offset:2496
	v_mul_f32_e32 v2, v14, v38
	v_cvt_pk_bf16_f32 v2, v2, s0
	ds_write_b16 v50, v2 offset:3072
	v_mul_f32_e32 v2, v30, v38
	v_cvt_pk_bf16_f32 v2, v2, s0
	v_rcp_f32_e32 v40, v40
	ds_write_b16 v50, v2 offset:3136
	v_mul_f32_e32 v2, v15, v39
	v_cvt_pk_bf16_f32 v2, v2, s0
	ds_write_b16 v50, v2 offset:3200
	v_mul_f32_e32 v2, v31, v39
	v_cvt_pk_bf16_f32 v2, v2, s0
	v_rcp_f32_e32 v41, v41
	ds_write_b16 v50, v2 offset:3264
	v_mul_f32_e32 v2, v16, v40
	v_cvt_pk_bf16_f32 v2, v2, s0
	ds_write_b16 v50, v2 offset:3328
	v_mul_f32_e32 v2, v32, v40
	v_cvt_pk_bf16_f32 v2, v2, s0
	ds_write_b16 v50, v2 offset:3392
	v_mul_f32_e32 v2, v17, v41
	v_cvt_pk_bf16_f32 v2, v2, s0
	ds_write_b16 v50, v2 offset:3456
	v_mul_f32_e32 v2, v33, v41
	v_cvt_pk_bf16_f32 v2, v2, s0
	ds_write_b16 v50, v2 offset:3520
	v_lshlrev_b32_e32 v2, 1, v87
	v_and_b32_e32 v206, 0x70, v2
	v_lshrrev_b32_e32 v14, 3, v85
	v_add_u32_e32 v15, s46, v206
	s_add_i32 s48, s48, s45
	s_waitcnt lgkmcnt(0)
	v_lshl_add_u32 v2, v14, 7, v15
	v_or_b32_e32 v6, s48, v14
	ds_read_b128 v[2:5], v2
	v_ashrrev_i32_e32 v7, 31, v6
	s_add_u32 s0, s0, s30
	v_lshlrev_b64 v[6:7], s44, v[6:7]
	s_addc_u32 s1, s1, s31
	v_lshl_add_u64 v[6:7], v[6:7], 0, s[28:29]
	v_lshl_add_u64 v[10:11], s[0:1], 0, v[206:207]
	v_lshlrev_b64 v[6:7], 10, v[6:7]
	v_or_b32_e32 v16, 8, v14
	v_lshl_add_u64 v[12:13], v[10:11], 0, v[6:7]
	v_lshl_add_u32 v6, v16, 7, v15
	ds_read_b128 v[6:9], v6
	s_waitcnt lgkmcnt(1)
	global_store_dwordx4 v[12:13], v[2:5], off sc1 nt
	s_nop 1
	v_or_b32_e32 v2, s48, v16
	v_ashrrev_i32_e32 v3, 31, v2
	v_lshlrev_b64 v[2:3], s44, v[2:3]
	v_lshl_add_u64 v[2:3], v[2:3], 0, s[28:29]
	v_lshlrev_b64 v[2:3], 10, v[2:3]
	v_lshl_add_u64 v[2:3], v[10:11], 0, v[2:3]
	s_waitcnt lgkmcnt(0)
	global_store_dwordx4 v[2:3], v[6:9], off sc1 nt
	s_nop 1
	v_or_b32_e32 v6, 16, v14
	v_lshl_add_u32 v2, v6, 7, v15
	v_or_b32_e32 v6, s48, v6
	ds_read_b128 v[2:5], v2
	v_ashrrev_i32_e32 v7, 31, v6
	v_lshlrev_b64 v[6:7], s44, v[6:7]
	v_lshl_add_u64 v[6:7], v[6:7], 0, s[28:29]
	v_lshlrev_b64 v[6:7], 10, v[6:7]
	v_or_b32_e32 v14, 24, v14
	v_lshl_add_u64 v[12:13], v[10:11], 0, v[6:7]
	v_lshl_add_u32 v6, v14, 7, v15
	ds_read_b128 v[6:9], v6
	s_waitcnt lgkmcnt(1)
	global_store_dwordx4 v[12:13], v[2:5], off sc1 nt
	s_nop 1
	v_or_b32_e32 v2, s48, v14
	v_ashrrev_i32_e32 v3, 31, v2
	v_lshlrev_b64 v[2:3], s44, v[2:3]
	v_lshl_add_u64 v[2:3], v[2:3], 0, s[28:29]
	v_lshlrev_b64 v[2:3], 10, v[2:3]
	v_lshl_add_u64 v[2:3], v[10:11], 0, v[2:3]
	s_waitcnt lgkmcnt(0)
	global_store_dwordx4 v[2:3], v[6:9], off sc1 nt
	s_barrier

.LBB0_384:
	v_add_f32_e32 v35, v52, v53
	v_add_f32_e32 v35, v54, v35
	v_add_f32_e32 v35, v55, v35
	v_add_f32_e32 v35, v56, v35
	v_add_f32_e32 v35, v57, v35
	v_add_f32_e32 v35, v58, v35
	v_add_f32_e32 v35, v59, v35
	v_add_f32_e32 v35, v60, v35
	v_add_f32_e32 v35, v61, v35
	v_add_f32_e32 v35, v62, v35
	v_add_f32_e32 v35, v63, v35
	v_add_f32_e32 v35, v64, v35
	v_add_f32_e32 v35, v65, v35
	v_add_f32_e32 v35, v66, v35
	v_add_f32_e32 v35, v67, v35
	v_add_f32_e32 v35, v36, v35
	v_add_f32_e32 v35, v37, v35
	v_add_f32_e32 v35, v38, v35
	v_add_f32_e32 v35, v39, v35
	v_add_f32_e32 v35, v40, v35
	v_add_f32_e32 v35, v41, v35
	v_add_f32_e32 v35, v42, v35
	v_add_f32_e32 v35, v43, v35
	v_add_f32_e32 v35, v44, v35
	v_add_f32_e32 v35, v45, v35
	v_add_f32_e32 v35, v46, v35
	v_add_f32_e32 v35, v47, v35
	v_add_f32_e32 v35, v48, v35
	v_add_f32_e32 v35, v49, v35
	s_cmp_lg_u32 0, -1
	v_add_f32_e32 v35, v50, v35
	s_cselect_b32 s0, 0, 0
	v_add_f32_e32 v35, v51, v35
	s_addk_i32 s0, 0x6000
	v_pk_mul_f32 v[32:33], v[210:211], v[32:33] op_sel_hi:[0,1]
	v_pk_mul_f32 v[30:31], v[210:211], v[30:31] op_sel_hi:[0,1]
	v_pk_mul_f32 v[28:29], v[210:211], v[28:29] op_sel_hi:[0,1]
	v_pk_mul_f32 v[26:27], v[210:211], v[26:27] op_sel_hi:[0,1]
	v_pk_mul_f32 v[24:25], v[210:211], v[24:25] op_sel_hi:[0,1]
	v_pk_mul_f32 v[22:23], v[210:211], v[22:23] op_sel_hi:[0,1]
	v_pk_mul_f32 v[20:21], v[210:211], v[20:21] op_sel_hi:[0,1]
	v_pk_mul_f32 v[18:19], v[210:211], v[18:19] op_sel_hi:[0,1]
	v_pk_mul_f32 v[16:17], v[210:211], v[16:17] op_sel_hi:[0,1]
	v_pk_mul_f32 v[14:15], v[210:211], v[14:15] op_sel_hi:[0,1]
	v_pk_mul_f32 v[12:13], v[210:211], v[12:13] op_sel_hi:[0,1]
	v_pk_mul_f32 v[10:11], v[210:211], v[10:11] op_sel_hi:[0,1]
	v_pk_mul_f32 v[8:9], v[210:211], v[8:9] op_sel_hi:[0,1]
	v_pk_mul_f32 v[6:7], v[210:211], v[6:7] op_sel_hi:[0,1]
	v_pk_mul_f32 v[4:5], v[210:211], v[4:5] op_sel_hi:[0,1]
	v_pk_mul_f32 v[2:3], v[210:211], v[2:3] op_sel_hi:[0,1]
	v_fmac_f32_e32 v35, v210, v34
	v_add3_u32 v68, v244, s0, v240
	v_cvt_pk_bf16_f32 v52, v52, v53
	v_cvt_pk_bf16_f32 v53, v54, v55
	v_cvt_pk_bf16_f32 v54, v56, v57
	v_cvt_pk_bf16_f32 v55, v58, v59
	v_cvt_pk_bf16_f32 v56, v60, v61
	v_cvt_pk_bf16_f32 v57, v62, v63
	v_cvt_pk_bf16_f32 v58, v64, v65
	v_cvt_pk_bf16_f32 v59, v66, v67
	v_cvt_pk_bf16_f32 v36, v36, v37
	v_cvt_pk_bf16_f32 v37, v38, v39
	v_cvt_pk_bf16_f32 v38, v40, v41
	v_cvt_pk_bf16_f32 v39, v42, v43
	v_cvt_pk_bf16_f32 v40, v44, v45
	v_cvt_pk_bf16_f32 v41, v46, v47
	v_cvt_pk_bf16_f32 v42, v48, v49
	v_cvt_pk_bf16_f32 v43, v50, v51
	v_add3_u32 v34, v68, v241, s46
	ds_read_b64_tr_b16 v[44:45],v34 offset:0
	ds_read_b64_tr_b16 v[46:47],v34 offset:512
	ds_read_b64_tr_b16 v[48:49],v34 offset:1024
	ds_read_b64_tr_b16 v[50:51],v34 offset:1536
	ds_read_b64_tr_b16 v[60:61],v34 offset:2048
	ds_read_b64_tr_b16 v[62:63],v34 offset:2560
	ds_read_b64_tr_b16 v[64:65],v34 offset:3072
	ds_read_b64_tr_b16 v[66:67],v34 offset:3584
	s_waitcnt lgkmcnt(0)
	s_nop 0
	v_mfma_f32_32x32x16_bf16 v[2:17], v[52:55], v[44:47], v[2:17]
	ds_read_b64_tr_b16 v[44:45],v34 offset:4096
	ds_read_b64_tr_b16 v[46:47],v34 offset:4608
	v_mfma_f32_32x32x16_bf16 v[2:17], v[56:59], v[48:51], v[2:17]
	ds_read_b64_tr_b16 v[48:49],v34 offset:5120
	ds_read_b64_tr_b16 v[50:51],v34 offset:5632
	v_mfma_f32_32x32x16_bf16 v[2:17], v[36:39], v[60:63], v[2:17]
	ds_read_b64_tr_b16 v[60:61],v34 offset:6144
	ds_read_b64_tr_b16 v[62:63],v34 offset:6656
	v_mfma_f32_32x32x16_bf16 v[2:17], v[40:43], v[64:67], v[2:17]
	ds_read_b64_tr_b16 v[64:65],v34 offset:7168
	ds_read_b64_tr_b16 v[66:67],v34 offset:7680
	s_waitcnt lgkmcnt(0)
	v_mfma_f32_32x32x16_bf16 v[18:33], v[52:55], v[44:47], v[18:33]
	v_mov_b32_e32 v34, v35
	s_nop 1
	v_permlane32_swap_b32_e32 v35, v34
	v_cmp_gt_u32_e32 vcc, 32, v209
	v_mfma_f32_32x32x16_bf16 v[18:33], v[56:59], v[48:51], v[18:33]
	v_mfma_f32_32x32x16_bf16 v[18:33], v[36:39], v[60:63], v[18:33]
	v_mfma_f32_32x32x16_bf16 v[18:33], v[40:43], v[64:67], v[18:33]
	s_and_saveexec_b64 s[0:1], vcc
	v_add_f32_e32 v34, v35, v34
	ds_write_b32 v243, v34 offset:49280
	s_or_b64 exec, exec, s[0:1]
	s_waitcnt lgkmcnt(0)
	ds_read_b128 v[34:37], v242 offset:49280
	ds_read_b128 v[38:41], v242 offset:49312
	s_lshl_b32 s0, s43, 12
	s_add_i32 s6, s0, 0
	v_lshlrev_b32_e32 v50, 1, v238
	s_waitcnt lgkmcnt(1)
	v_rcp_f32_e32 v42, v34
	v_rcp_f32_e32 v43, v35
	v_lshlrev_b32_e32 v51, 9, v239
	v_add3_u32 v50, s6, v50, v51
	v_mul_f32_e32 v2, v2, v42
	v_cvt_pk_bf16_f32 v2, v2, s0
	v_rcp_f32_e32 v44, v36
	v_rcp_f32_e32 v45, v37
	s_waitcnt lgkmcnt(0)
	v_rcp_f32_e32 v46, v38
	ds_read_b128 v[34:37], v242 offset:49344
	v_rcp_f32_e32 v47, v39
	v_rcp_f32_e32 v48, v40
	v_rcp_f32_e32 v49, v41
	ds_read_b128 v[38:41], v242 offset:49376
	ds_write_b16 v50, v2 offset:51200
	v_mul_f32_e32 v2, v18, v42
	v_cvt_pk_bf16_f32 v2, v2, s0
	ds_write_b16 v50, v2 offset:51264
	v_mul_f32_e32 v2, v3, v43
	v_cvt_pk_bf16_f32 v2, v2, s0
	ds_write_b16 v50, v2 offset:51328
	v_mul_f32_e32 v2, v19, v43
	v_cvt_pk_bf16_f32 v2, v2, s0
	ds_write_b16 v50, v2 offset:51392
	v_mul_f32_e32 v2, v4, v44
	v_cvt_pk_bf16_f32 v2, v2, s0
	ds_write_b16 v50, v2 offset:51456
	v_mul_f32_e32 v2, v20, v44
	v_cvt_pk_bf16_f32 v2, v2, s0
	ds_write_b16 v50, v2 offset:51520
	v_mul_f32_e32 v2, v5, v45
	v_cvt_pk_bf16_f32 v2, v2, s0
	ds_write_b16 v50, v2 offset:51584
	v_mul_f32_e32 v2, v21, v45
	v_cvt_pk_bf16_f32 v2, v2, s0
	ds_write_b16 v50, v2 offset:51648
	v_mul_f32_e32 v2, v6, v46
	v_cvt_pk_bf16_f32 v2, v2, s0
	ds_write_b16 v50, v2 offset:52224
	v_mul_f32_e32 v2, v22, v46
	v_cvt_pk_bf16_f32 v2, v2, s0
	ds_write_b16 v50, v2 offset:52288
	v_mul_f32_e32 v2, v7, v47
	v_cvt_pk_bf16_f32 v2, v2, s0
	ds_write_b16 v50, v2 offset:52352
	v_mul_f32_e32 v2, v23, v47
	v_cvt_pk_bf16_f32 v2, v2, s0
	ds_write_b16 v50, v2 offset:52416
	v_mul_f32_e32 v2, v8, v48
	v_cvt_pk_bf16_f32 v2, v2, s0
	ds_write_b16 v50, v2 offset:52480
	v_mul_f32_e32 v2, v24, v48
	v_cvt_pk_bf16_f32 v2, v2, s0
	s_waitcnt lgkmcnt(14)
	v_rcp_f32_e32 v34, v34
	ds_write_b16 v50, v2 offset:52544
	v_mul_f32_e32 v2, v9, v49
	v_cvt_pk_bf16_f32 v2, v2, s0
	ds_write_b16 v50, v2 offset:52608
	v_mul_f32_e32 v2, v25, v49
	v_cvt_pk_bf16_f32 v2, v2, s0
	v_rcp_f32_e32 v35, v35
	ds_write_b16 v50, v2 offset:52672
	v_mul_f32_e32 v2, v10, v34
	v_cvt_pk_bf16_f32 v2, v2, s0
	ds_write_b16 v50, v2 offset:53248
	v_mul_f32_e32 v2, v26, v34
	v_cvt_pk_bf16_f32 v2, v2, s0
	v_rcp_f32_e32 v36, v36
	ds_write_b16 v50, v2 offset:53312
	v_mul_f32_e32 v2, v11, v35
	v_cvt_pk_bf16_f32 v2, v2, s0
	ds_write_b16 v50, v2 offset:53376
	v_mul_f32_e32 v2, v27, v35
	v_cvt_pk_bf16_f32 v2, v2, s0
	v_rcp_f32_e32 v37, v37
	ds_write_b16 v50, v2 offset:53440
	v_mul_f32_e32 v2, v12, v36
	v_cvt_pk_bf16_f32 v2, v2, s0
	ds_write_b16 v50, v2 offset:53504
	v_mul_f32_e32 v2, v28, v36
	v_cvt_pk_bf16_f32 v2, v2, s0
	s_waitcnt lgkmcnt(14)
	v_rcp_f32_e32 v38, v38
	ds_write_b16 v50, v2 offset:53568
	v_mul_f32_e32 v2, v13, v37
	v_cvt_pk_bf16_f32 v2, v2, s0
	ds_write_b16 v50, v2 offset:53632
	v_mul_f32_e32 v2, v29, v37
	v_cvt_pk_bf16_f32 v2, v2, s0
	v_rcp_f32_e32 v39, v39
	ds_write_b16 v50, v2 offset:53696
	v_mul_f32_e32 v2, v14, v38
	v_cvt_pk_bf16_f32 v2, v2, s0
	ds_write_b16 v50, v2 offset:54272
	v_mul_f32_e32 v2, v30, v38
	v_cvt_pk_bf16_f32 v2, v2, s0
	v_rcp_f32_e32 v40, v40
	ds_write_b16 v50, v2 offset:54336
	v_mul_f32_e32 v2, v15, v39
	v_cvt_pk_bf16_f32 v2, v2, s0
	ds_write_b16 v50, v2 offset:54400
	v_mul_f32_e32 v2, v31, v39
	v_cvt_pk_bf16_f32 v2, v2, s0
	v_rcp_f32_e32 v41, v41
	ds_write_b16 v50, v2 offset:54464
	v_mul_f32_e32 v2, v16, v40
	v_cvt_pk_bf16_f32 v2, v2, s0
	ds_write_b16 v50, v2 offset:54528
	v_mul_f32_e32 v2, v32, v40
	v_cvt_pk_bf16_f32 v2, v2, s0
	ds_write_b16 v50, v2 offset:54592
	v_mul_f32_e32 v2, v17, v41
	v_cvt_pk_bf16_f32 v2, v2, s0
	ds_write_b16 v50, v2 offset:54656
	v_mul_f32_e32 v2, v33, v41
	v_cvt_pk_bf16_f32 v2, v2, s0
	ds_write_b16 v50, v2 offset:54720
	v_lshlrev_b32_e32 v2, 1, v237
	v_and_b32_e32 v206, 0x70, v2
	s_ashr_i32 s29, s28, 31
	s_lshl_b64 s[0:1], s[30:31], 1
	v_lshrrev_b32_e32 v14, 3, v209
	v_add_u32_e32 v15, s6, v206
	s_add_u32 s7, s56, s0
	s_waitcnt lgkmcnt(0)
	v_lshl_add_u32 v2, v14, 7, v15
	v_or_b32_e32 v16, 8, v14
	s_addc_u32 s10, s57, s1
	s_lshl_b64 s[0:1], s[28:29], 1
	ds_read_b128 v[2:5], v2 offset:51200
	v_lshl_add_u32 v6, v16, 7, v15
	s_add_u32 s0, s7, s0
	ds_read_b128 v[6:9], v6 offset:51200
	s_addc_u32 s1, s10, s1
	v_lshl_add_u64 v[10:11], s[0:1], 0, v[206:207]
	v_lshlrev_b32_e32 v206, 11, v14
	v_lshl_add_u64 v[12:13], v[10:11], 0, v[206:207]
	v_lshlrev_b32_e32 v206, 11, v16
	s_waitcnt lgkmcnt(1)
	global_store_dwordx4 v[12:13], v[2:5], off sc1 nt
	v_mov_b32_e32 v84, v236
	s_nop 0
	v_lshl_add_u64 v[2:3], v[10:11], 0, v[206:207]
	s_waitcnt lgkmcnt(0)
	global_store_dwordx4 v[2:3], v[6:9], off sc1 nt
	s_nop 1
	v_or_b32_e32 v6, 16, v14
	v_lshl_add_u32 v2, v6, 7, v15
	v_or_b32_e32 v14, 24, v14
	ds_read_b128 v[2:5], v2 offset:51200
	v_lshlrev_b32_e32 v206, 11, v6
	v_lshl_add_u32 v6, v14, 7, v15
	ds_read_b128 v[6:9], v6 offset:51200
	v_lshl_add_u64 v[12:13], v[10:11], 0, v[206:207]
	v_lshlrev_b32_e32 v206, 11, v14
	s_waitcnt lgkmcnt(1)
	global_store_dwordx4 v[12:13], v[2:5], off sc1 nt
	s_nop 1
	v_lshl_add_u64 v[2:3], v[10:11], 0, v[206:207]
	s_waitcnt lgkmcnt(0)
	global_store_dwordx4 v[2:3], v[6:9], off sc1 nt
	s_waitcnt lgkmcnt(0)
	s_barrier
	s_and_saveexec_b64 s[0:1], s[14:15]
	s_cbranch_execz .LBB0_330
